# residual GEMM epilogue (out-proj / FF2 tiles) hand-written: the 32 residual loads of a tile pipelined instead of 32 dependent round trips
# speedup vs baseline: 1.5870x; 1.0293x over previous
.LBB0_241:
	s_add_i32 s39, s13, s47
	s_cmp_lt_i32 s39, 4
	s_cselect_b64 s[40:41], -1, 0
	s_lshl_b32 s78, s39, 8
	s_add_i32 s79, s78, 0xfffffc00
	s_and_b64 s[42:43], s[40:41], exec
	s_cselect_b32 s42, s78, s79
	v_add_u32_e32 v128, s42, v206
	s_add_i32 s39, s39, -4
	v_ashrrev_i32_e32 v129, 31, v128
	s_lshr_b32 s39, s39, 4
	v_lshlrev_b64 v[128:129], 10, v[128:129]
	s_and_b64 s[40:41], s[40:41], exec
	v_lshl_add_u64 v[128:129], v[128:129], 0, v[150:151]
	s_cselect_b32 s41, s26, s95
	s_cselect_b32 s40, s27, s44
	v_lshlrev_b64 v[128:129], 2, v[128:129]
	v_lshl_add_u64 v[154:155], s[40:41], 0, v[128:129]
	v_readlane_b32 s40, v247, 29
	v_readlane_b32 s41, v247, 30
	s_cselect_b32 s41, s72, s41
	s_cselect_b32 s40, s71, s40
	s_cselect_b32 s39, 4, s39
	v_lshl_add_u64 v[152:153], s[40:41], 0, v[128:129]
	s_mul_i32 s40, s70, 5
	s_add_i32 s39, s39, s40
	s_mul_i32 s40, s39, 0x1800
	s_ashr_i32 s41, s40, 31
	s_lshl_b64 s[40:41], s[40:41], 2
	s_add_u32 s40, s45, s40
	v_lshlrev_b64 v[132:133], 2, v[150:151]
	s_addc_u32 s41, s58, s41
	v_lshl_add_u64 v[156:157], s[10:11], 0, v[132:133]
	v_lshl_add_u64 v[158:159], s[40:41], 0, v[132:133]
	global_load_dwordx4 v[176:179], v[156:157], off offset:0
	global_load_dwordx4 v[180:183], v[156:157], off offset:64
	global_load_dwordx4 v[210:213], v[156:157], off offset:512
	global_load_dwordx4 v[214:217], v[156:157], off offset:576
	global_load_dwordx4 v[160:163], v[158:159], off offset:0
	global_load_dwordx4 v[164:167], v[158:159], off offset:64
	global_load_dwordx4 v[168:171], v[158:159], off offset:512
	global_load_dwordx4 v[172:175], v[158:159], off offset:576
	global_load_dwordx4 v[132:135], v[154:155], off offset:0
	global_load_dwordx4 v[156:159], v[154:155], off offset:64
	s_waitcnt vmcnt(6)
	v_pk_add_f32 v[126:127], v[126:127], v[178:179]
	v_pk_add_f32 v[124:125], v[124:125], v[176:177]
	v_pk_add_f32 v[122:123], v[122:123], v[178:179]
	v_pk_add_f32 v[120:121], v[120:121], v[176:177]
	v_pk_add_f32 v[118:119], v[118:119], v[178:179]
	v_pk_add_f32 v[116:117], v[116:117], v[176:177]
	v_pk_add_f32 v[114:115], v[114:115], v[178:179]
	v_pk_add_f32 v[112:113], v[112:113], v[176:177]
	v_pk_add_f32 v[110:111], v[110:111], v[178:179]
	v_pk_add_f32 v[108:109], v[108:109], v[176:177]
	v_pk_add_f32 v[106:107], v[106:107], v[178:179]
	v_pk_add_f32 v[104:105], v[104:105], v[176:177]
	v_pk_add_f32 v[102:103], v[102:103], v[178:179]
	v_pk_add_f32 v[100:101], v[100:101], v[176:177]
	v_pk_add_f32 v[98:99], v[98:99], v[178:179]
	v_pk_add_f32 v[96:97], v[96:97], v[176:177]
	v_pk_add_f32 v[94:95], v[94:95], v[182:183]
	v_pk_add_f32 v[92:93], v[92:93], v[180:181]
	v_pk_add_f32 v[90:91], v[90:91], v[182:183]
	v_pk_add_f32 v[88:89], v[88:89], v[180:181]
	v_pk_add_f32 v[86:87], v[86:87], v[182:183]
	v_pk_add_f32 v[84:85], v[84:85], v[180:181]
	v_pk_add_f32 v[82:83], v[82:83], v[182:183]
	v_pk_add_f32 v[80:81], v[80:81], v[180:181]
	v_pk_add_f32 v[78:79], v[78:79], v[182:183]
	v_pk_add_f32 v[76:77], v[76:77], v[180:181]
	v_pk_add_f32 v[74:75], v[74:75], v[182:183]
	v_pk_add_f32 v[72:73], v[72:73], v[180:181]
	v_pk_add_f32 v[70:71], v[70:71], v[182:183]
	v_pk_add_f32 v[68:69], v[68:69], v[180:181]
	v_pk_add_f32 v[66:67], v[66:67], v[182:183]
	v_pk_add_f32 v[64:65], v[64:65], v[180:181]
	v_pk_add_f32 v[62:63], v[62:63], v[212:213]
	v_pk_add_f32 v[60:61], v[60:61], v[210:211]
	v_pk_add_f32 v[58:59], v[58:59], v[212:213]
	v_pk_add_f32 v[56:57], v[56:57], v[210:211]
	v_pk_add_f32 v[54:55], v[54:55], v[212:213]
	v_pk_add_f32 v[52:53], v[52:53], v[210:211]
	v_pk_add_f32 v[50:51], v[50:51], v[212:213]
	v_pk_add_f32 v[48:49], v[48:49], v[210:211]
	v_pk_add_f32 v[46:47], v[46:47], v[212:213]
	v_pk_add_f32 v[44:45], v[44:45], v[210:211]
	v_pk_add_f32 v[42:43], v[42:43], v[212:213]
	v_pk_add_f32 v[40:41], v[40:41], v[210:211]
	v_pk_add_f32 v[38:39], v[38:39], v[212:213]
	v_pk_add_f32 v[36:37], v[36:37], v[210:211]
	v_pk_add_f32 v[34:35], v[34:35], v[212:213]
	v_pk_add_f32 v[32:33], v[32:33], v[210:211]
	v_pk_add_f32 v[30:31], v[30:31], v[216:217]
	v_pk_add_f32 v[28:29], v[28:29], v[214:215]
	v_pk_add_f32 v[26:27], v[26:27], v[216:217]
	v_pk_add_f32 v[24:25], v[24:25], v[214:215]
	v_pk_add_f32 v[22:23], v[22:23], v[216:217]
	v_pk_add_f32 v[20:21], v[20:21], v[214:215]
	v_pk_add_f32 v[18:19], v[18:19], v[216:217]
	v_pk_add_f32 v[16:17], v[16:17], v[214:215]
	v_pk_add_f32 v[14:15], v[14:15], v[216:217]
	v_pk_add_f32 v[12:13], v[12:13], v[214:215]
	v_pk_add_f32 v[10:11], v[10:11], v[216:217]
	v_pk_add_f32 v[8:9], v[8:9], v[214:215]
	v_pk_add_f32 v[6:7], v[6:7], v[216:217]
	v_pk_add_f32 v[4:5], v[4:5], v[214:215]
	v_pk_add_f32 v[2:3], v[2:3], v[216:217]
	v_pk_add_f32 v[0:1], v[0:1], v[214:215]
	global_load_dwordx4 v[176:179], v[154:155], off offset:512
	global_load_dwordx4 v[180:183], v[154:155], off offset:576
	s_mov_b64 s[78:79], 0x10000
	v_lshl_add_u64 v[128:129], v[154:155], 0, s[78:79]
	global_load_dwordx4 v[210:213], v[128:129], off offset:0
	global_load_dwordx4 v[214:217], v[128:129], off offset:64
	s_waitcnt vmcnt(6)
	s_waitcnt vmcnt(5)
	v_pk_fma_f32 v[134:135], v[162:163], v[126:127], v[134:135]
	v_pk_fma_f32 v[132:133], v[160:161], v[124:125], v[132:133]
	global_store_dwordx4 v[152:153], v[132:135], off offset:0
	global_load_dwordx4 v[132:135], v[128:129], off offset:512
	global_load_dwordx4 v[124:127], v[128:129], off offset:576
	s_waitcnt vmcnt(7)
	v_pk_fma_f32 v[158:159], v[166:167], v[94:95], v[158:159]
	v_pk_fma_f32 v[156:157], v[164:165], v[92:93], v[156:157]
	global_store_dwordx4 v[152:153], v[156:159], off offset:64
	s_mov_b64 s[78:79], 0x20000
	v_lshl_add_u64 v[128:129], v[154:155], 0, s[78:79]
	global_load_dwordx4 v[156:159], v[128:129], off offset:0
	global_load_dwordx4 v[92:95], v[128:129], off offset:64
	s_waitcnt vmcnt(9)
	v_pk_fma_f32 v[178:179], v[170:171], v[62:63], v[178:179]
	v_pk_fma_f32 v[176:177], v[168:169], v[60:61], v[176:177]
	global_store_dwordx4 v[152:153], v[176:179], off offset:512
	global_load_dwordx4 v[176:179], v[128:129], off offset:512
	global_load_dwordx4 v[60:63], v[128:129], off offset:576
	s_waitcnt vmcnt(11)
	v_pk_fma_f32 v[182:183], v[174:175], v[30:31], v[182:183]
	v_pk_fma_f32 v[180:181], v[172:173], v[28:29], v[180:181]
	global_store_dwordx4 v[152:153], v[180:183], off offset:576
	s_mov_b64 s[78:79], 0x30000
	v_lshl_add_u64 v[128:129], v[154:155], 0, s[78:79]
	global_load_dwordx4 v[180:183], v[128:129], off offset:0
	global_load_dwordx4 v[28:31], v[128:129], off offset:64
	s_waitcnt vmcnt(13)
	v_pk_fma_f32 v[212:213], v[162:163], v[122:123], v[212:213]
	v_pk_fma_f32 v[210:211], v[160:161], v[120:121], v[210:211]
	s_mov_b64 s[42:43], 0x10000
	v_lshl_add_u64 v[130:131], v[152:153], 0, s[42:43]
	global_store_dwordx4 v[130:131], v[210:213], off offset:0
	global_load_dwordx4 v[210:213], v[128:129], off offset:512
	global_load_dwordx4 v[120:123], v[128:129], off offset:576
	s_waitcnt vmcnt(15)
	v_pk_fma_f32 v[216:217], v[166:167], v[90:91], v[216:217]
	v_pk_fma_f32 v[214:215], v[164:165], v[88:89], v[214:215]
	global_store_dwordx4 v[130:131], v[214:217], off offset:64
	s_mov_b64 s[78:79], 0x80000
	v_lshl_add_u64 v[128:129], v[154:155], 0, s[78:79]
	global_load_dwordx4 v[214:217], v[128:129], off offset:0
	global_load_dwordx4 v[88:91], v[128:129], off offset:64
	s_waitcnt vmcnt(16)
	v_pk_fma_f32 v[134:135], v[170:171], v[58:59], v[134:135]
	v_pk_fma_f32 v[132:133], v[168:169], v[56:57], v[132:133]
	global_store_dwordx4 v[130:131], v[132:135], off offset:512
	global_load_dwordx4 v[132:135], v[128:129], off offset:512
	global_load_dwordx4 v[56:59], v[128:129], off offset:576
	s_waitcnt vmcnt(18)
	v_pk_fma_f32 v[126:127], v[174:175], v[26:27], v[126:127]
	v_pk_fma_f32 v[124:125], v[172:173], v[24:25], v[124:125]
	global_store_dwordx4 v[130:131], v[124:127], off offset:576
	s_mov_b64 s[78:79], 0x90000
	v_lshl_add_u64 v[128:129], v[154:155], 0, s[78:79]
	global_load_dwordx4 v[124:127], v[128:129], off offset:0
	global_load_dwordx4 v[24:27], v[128:129], off offset:64
	s_waitcnt vmcnt(19)
	v_pk_fma_f32 v[158:159], v[162:163], v[118:119], v[158:159]
	v_pk_fma_f32 v[156:157], v[160:161], v[116:117], v[156:157]
	s_mov_b64 s[42:43], 0x20000
	v_lshl_add_u64 v[130:131], v[152:153], 0, s[42:43]
	global_store_dwordx4 v[130:131], v[156:159], off offset:0
	global_load_dwordx4 v[156:159], v[128:129], off offset:512
	s_waitcnt vmcnt(20)
	v_pk_fma_f32 v[94:95], v[166:167], v[86:87], v[94:95]
	v_pk_fma_f32 v[92:93], v[164:165], v[84:85], v[92:93]
	global_store_dwordx4 v[130:131], v[92:95], off offset:64
	global_load_dwordx4 v[116:119], v[128:129], off offset:576
	s_waitcnt vmcnt(20)
	v_pk_fma_f32 v[178:179], v[170:171], v[54:55], v[178:179]
	v_pk_fma_f32 v[176:177], v[168:169], v[52:53], v[176:177]
	global_store_dwordx4 v[130:131], v[176:179], off offset:512
	s_mov_b64 s[78:79], 0xa0000
	v_lshl_add_u64 v[128:129], v[154:155], 0, s[78:79]
	global_load_dwordx4 v[92:95], v[128:129], off offset:0
	s_waitcnt vmcnt(21)
	v_pk_fma_f32 v[62:63], v[174:175], v[22:23], v[62:63]
	v_pk_fma_f32 v[60:61], v[172:173], v[20:21], v[60:61]
	global_store_dwordx4 v[130:131], v[60:63], off offset:576
	global_load_dwordx4 v[84:87], v[128:129], off offset:64
	s_waitcnt vmcnt(21)
	v_pk_fma_f32 v[182:183], v[162:163], v[114:115], v[182:183]
	v_pk_fma_f32 v[180:181], v[160:161], v[112:113], v[180:181]
	s_mov_b64 s[42:43], 0x30000
	v_lshl_add_u64 v[130:131], v[152:153], 0, s[42:43]
	global_store_dwordx4 v[130:131], v[180:183], off offset:0
	global_load_dwordx4 v[176:179], v[128:129], off offset:512
	s_waitcnt vmcnt(22)
	v_pk_fma_f32 v[30:31], v[166:167], v[82:83], v[30:31]
	v_pk_fma_f32 v[28:29], v[164:165], v[80:81], v[28:29]
	global_store_dwordx4 v[130:131], v[28:31], off offset:64
	global_load_dwordx4 v[52:55], v[128:129], off offset:576
	s_waitcnt vmcnt(22)
	v_pk_fma_f32 v[212:213], v[170:171], v[50:51], v[212:213]
	v_pk_fma_f32 v[210:211], v[168:169], v[48:49], v[210:211]
	global_store_dwordx4 v[130:131], v[210:213], off offset:512
	s_mov_b64 s[78:79], 0xb0000
	v_lshl_add_u64 v[128:129], v[154:155], 0, s[78:79]
	global_load_dwordx4 v[60:63], v[128:129], off offset:0
	s_waitcnt vmcnt(23)
	v_pk_fma_f32 v[122:123], v[174:175], v[18:19], v[122:123]
	v_pk_fma_f32 v[120:121], v[172:173], v[16:17], v[120:121]
	global_store_dwordx4 v[130:131], v[120:123], off offset:576
	global_load_dwordx4 v[20:23], v[128:129], off offset:64
	s_waitcnt vmcnt(23)
	v_pk_fma_f32 v[216:217], v[162:163], v[110:111], v[216:217]
	v_pk_fma_f32 v[214:215], v[160:161], v[108:109], v[214:215]
	s_mov_b64 s[42:43], 0x80000
	v_lshl_add_u64 v[130:131], v[152:153], 0, s[42:43]
	global_store_dwordx4 v[130:131], v[214:217], off offset:0
	global_load_dwordx4 v[180:183], v[128:129], off offset:512
	s_waitcnt vmcnt(24)
	v_pk_fma_f32 v[90:91], v[166:167], v[78:79], v[90:91]
	v_pk_fma_f32 v[88:89], v[164:165], v[76:77], v[88:89]
	global_store_dwordx4 v[130:131], v[88:91], off offset:64
	global_load_dwordx4 v[112:115], v[128:129], off offset:576
	s_waitcnt vmcnt(24)
	v_pk_fma_f32 v[134:135], v[170:171], v[46:47], v[134:135]
	v_pk_fma_f32 v[132:133], v[168:169], v[44:45], v[132:133]
	global_store_dwordx4 v[130:131], v[132:135], off offset:512
	s_waitcnt vmcnt(24)
	v_pk_fma_f32 v[58:59], v[174:175], v[14:15], v[58:59]
	v_pk_fma_f32 v[56:57], v[172:173], v[12:13], v[56:57]
	global_store_dwordx4 v[130:131], v[56:59], off offset:576
	s_waitcnt vmcnt(23)
	v_pk_fma_f32 v[126:127], v[162:163], v[106:107], v[126:127]
	v_pk_fma_f32 v[124:125], v[160:161], v[104:105], v[124:125]
	s_mov_b64 s[42:43], 0x90000
	v_lshl_add_u64 v[130:131], v[152:153], 0, s[42:43]
	global_store_dwordx4 v[130:131], v[124:127], off offset:0
	s_waitcnt vmcnt(23)
	v_pk_fma_f32 v[26:27], v[166:167], v[74:75], v[26:27]
	v_pk_fma_f32 v[24:25], v[164:165], v[72:73], v[24:25]
	global_store_dwordx4 v[130:131], v[24:27], off offset:64
	s_waitcnt vmcnt(22)
	v_pk_fma_f32 v[158:159], v[170:171], v[42:43], v[158:159]
	v_pk_fma_f32 v[156:157], v[168:169], v[40:41], v[156:157]
	global_store_dwordx4 v[130:131], v[156:159], off offset:512
	s_waitcnt vmcnt(21)
	v_pk_fma_f32 v[118:119], v[174:175], v[10:11], v[118:119]
	v_pk_fma_f32 v[116:117], v[172:173], v[8:9], v[116:117]
	global_store_dwordx4 v[130:131], v[116:119], off offset:576
	s_waitcnt vmcnt(20)
	v_pk_fma_f32 v[94:95], v[162:163], v[102:103], v[94:95]
	v_pk_fma_f32 v[92:93], v[160:161], v[100:101], v[92:93]
	s_mov_b64 s[42:43], 0xa0000
	v_lshl_add_u64 v[130:131], v[152:153], 0, s[42:43]
	global_store_dwordx4 v[130:131], v[92:95], off offset:0
	s_waitcnt vmcnt(19)
	v_pk_fma_f32 v[86:87], v[166:167], v[70:71], v[86:87]
	v_pk_fma_f32 v[84:85], v[164:165], v[68:69], v[84:85]
	global_store_dwordx4 v[130:131], v[84:87], off offset:64
	s_waitcnt vmcnt(18)
	v_pk_fma_f32 v[178:179], v[170:171], v[38:39], v[178:179]
	v_pk_fma_f32 v[176:177], v[168:169], v[36:37], v[176:177]
	global_store_dwordx4 v[130:131], v[176:179], off offset:512
	s_waitcnt vmcnt(17)
	v_pk_fma_f32 v[54:55], v[174:175], v[6:7], v[54:55]
	v_pk_fma_f32 v[52:53], v[172:173], v[4:5], v[52:53]
	global_store_dwordx4 v[130:131], v[52:55], off offset:576
	s_waitcnt vmcnt(16)
	v_pk_fma_f32 v[62:63], v[162:163], v[98:99], v[62:63]
	v_pk_fma_f32 v[60:61], v[160:161], v[96:97], v[60:61]
	s_mov_b64 s[42:43], 0xb0000
	v_lshl_add_u64 v[130:131], v[152:153], 0, s[42:43]
	global_store_dwordx4 v[130:131], v[60:63], off offset:0
	s_waitcnt vmcnt(15)
	v_pk_fma_f32 v[22:23], v[166:167], v[66:67], v[22:23]
	v_pk_fma_f32 v[20:21], v[164:165], v[64:65], v[20:21]
	global_store_dwordx4 v[130:131], v[20:23], off offset:64
	s_waitcnt vmcnt(14)
	v_pk_fma_f32 v[182:183], v[170:171], v[34:35], v[182:183]
	v_pk_fma_f32 v[180:181], v[168:169], v[32:33], v[180:181]
	global_store_dwordx4 v[130:131], v[180:183], off offset:512
	s_waitcnt vmcnt(13)
	v_pk_fma_f32 v[114:115], v[174:175], v[2:3], v[114:115]
	v_pk_fma_f32 v[112:113], v[172:173], v[0:1], v[112:113]
	global_store_dwordx4 v[130:131], v[112:115], off offset:576
	s_cbranch_execnz .LBB0_240
